# scan loop: rows-in-pk layout (row pair per packed lane, column scalars via op_sel), fewer VALU ops per step
# baseline (speedup 1.0000x reference)
.Lscan_iter:
	ds_read_b128 v[26:29], v118 offset:40960
	ds_read_b128 v[30:33], v118 offset:40976
	ds_read_b128 v[76:79], v118 offset:16384
	ds_read_b128 v[80:83], v118 offset:16400
	ds_read2_b32 v[34:35], v119 offset0:0 offset1:32
	ds_read2_b32 v[0:1], v121 offset0:0 offset1:32
	ds_read_b128 v[18:21], v118 offset:8192
	ds_read_b128 v[22:25], v118 offset:8208
	s_waitcnt lgkmcnt(8)
	v_pk_mul_f32 v[84:85], v[60:61], v[2:3] op_sel:[0,0] op_sel_hi:[1,0]
	v_pk_mul_f32 v[86:87], v[60:61], v[10:11] op_sel:[0,0] op_sel_hi:[1,0]
	v_pk_fma_f32 v[84:85], v[62:63], v[2:3], v[84:85] op_sel:[0,1,0] op_sel_hi:[1,1,1]
	v_pk_fma_f32 v[86:87], v[62:63], v[10:11], v[86:87] op_sel:[0,1,0] op_sel_hi:[1,1,1]
	v_pk_fma_f32 v[84:85], v[64:65], v[4:5], v[84:85] op_sel:[0,0,0] op_sel_hi:[1,0,1]
	v_pk_fma_f32 v[86:87], v[64:65], v[12:13], v[86:87] op_sel:[0,0,0] op_sel_hi:[1,0,1]
	v_pk_fma_f32 v[84:85], v[66:67], v[4:5], v[84:85] op_sel:[0,1,0] op_sel_hi:[1,1,1]
	v_pk_fma_f32 v[86:87], v[66:67], v[12:13], v[86:87] op_sel:[0,1,0] op_sel_hi:[1,1,1]
	v_pk_fma_f32 v[84:85], v[68:69], v[6:7], v[84:85] op_sel:[0,0,0] op_sel_hi:[1,0,1]
	v_pk_fma_f32 v[86:87], v[68:69], v[14:15], v[86:87] op_sel:[0,0,0] op_sel_hi:[1,0,1]
	v_pk_fma_f32 v[84:85], v[70:71], v[6:7], v[84:85] op_sel:[0,1,0] op_sel_hi:[1,1,1]
	v_pk_fma_f32 v[86:87], v[70:71], v[14:15], v[86:87] op_sel:[0,1,0] op_sel_hi:[1,1,1]
	v_pk_fma_f32 v[84:85], v[72:73], v[8:9], v[84:85] op_sel:[0,0,0] op_sel_hi:[1,0,1]
	v_pk_fma_f32 v[86:87], v[72:73], v[16:17], v[86:87] op_sel:[0,0,0] op_sel_hi:[1,0,1]
	v_pk_fma_f32 v[84:85], v[74:75], v[8:9], v[84:85] op_sel:[0,1,0] op_sel_hi:[1,1,1]
	v_pk_fma_f32 v[86:87], v[74:75], v[16:17], v[86:87] op_sel:[0,1,0] op_sel_hi:[1,1,1]
	v_add_f32_dpp v84, v84, v84 quad_perm:[1,0,3,2] row_mask:0xf bank_mask:0xf bound_ctrl:1
	v_add_f32_dpp v85, v85, v85 quad_perm:[1,0,3,2] row_mask:0xf bank_mask:0xf bound_ctrl:1
	v_add_f32_dpp v86, v86, v86 quad_perm:[1,0,3,2] row_mask:0xf bank_mask:0xf bound_ctrl:1
	v_add_f32_dpp v87, v87, v87 quad_perm:[1,0,3,2] row_mask:0xf bank_mask:0xf bound_ctrl:1
	v_add_f32_dpp v84, v84, v84 quad_perm:[2,3,0,1] row_mask:0xf bank_mask:0xf bound_ctrl:1
	v_add_f32_dpp v85, v85, v85 quad_perm:[2,3,0,1] row_mask:0xf bank_mask:0xf bound_ctrl:1
	v_add_f32_dpp v86, v86, v86 quad_perm:[2,3,0,1] row_mask:0xf bank_mask:0xf bound_ctrl:1
	v_add_f32_dpp v87, v87, v87 quad_perm:[2,3,0,1] row_mask:0xf bank_mask:0xf bound_ctrl:1
	v_add_f32_dpp v84, v84, v84 row_half_mirror row_mask:0xf bank_mask:0xf bound_ctrl:1
	v_add_f32_dpp v85, v85, v85 row_half_mirror row_mask:0xf bank_mask:0xf bound_ctrl:1
	v_add_f32_dpp v86, v86, v86 row_half_mirror row_mask:0xf bank_mask:0xf bound_ctrl:1
	v_add_f32_dpp v87, v87, v87 row_half_mirror row_mask:0xf bank_mask:0xf bound_ctrl:1
	ds_read_b128 v[2:5], v118 offset:33024
	ds_read_b128 v[6:9], v118 offset:33040
	ds_read_b128 v[10:13], v118 offset:256
	ds_read_b128 v[14:17], v118 offset:272
	s_waitcnt lgkmcnt(10)
	v_pk_mul_f32 v[114:115], v[26:27], v[84:85] op_sel:[0,0] op_sel_hi:[0,1] neg_lo:[0,1] neg_hi:[0,1]
	v_pk_mul_f32 v[116:117], v[26:27], v[84:85] op_sel:[1,0] op_sel_hi:[1,1] neg_lo:[0,1] neg_hi:[0,1]
	v_pk_mul_f32 v[122:123], v[28:29], v[84:85] op_sel:[0,0] op_sel_hi:[0,1] neg_lo:[0,1] neg_hi:[0,1]
	v_pk_mul_f32 v[124:125], v[28:29], v[84:85] op_sel:[1,0] op_sel_hi:[1,1] neg_lo:[0,1] neg_hi:[0,1]
	v_pk_mul_f32 v[126:127], v[30:31], v[84:85] op_sel:[0,0] op_sel_hi:[0,1] neg_lo:[0,1] neg_hi:[0,1]
	v_pk_mul_f32 v[128:129], v[30:31], v[84:85] op_sel:[1,0] op_sel_hi:[1,1] neg_lo:[0,1] neg_hi:[0,1]
	v_pk_mul_f32 v[130:131], v[32:33], v[84:85] op_sel:[0,0] op_sel_hi:[0,1] neg_lo:[0,1] neg_hi:[0,1]
	v_pk_mul_f32 v[132:133], v[32:33], v[84:85] op_sel:[1,0] op_sel_hi:[1,1] neg_lo:[0,1] neg_hi:[0,1]
	s_waitcnt lgkmcnt(7)
	v_pk_fma_f32 v[114:115], v[76:77], v[34:35], v[114:115] op_sel:[0,0,0] op_sel_hi:[0,1,1]
	v_pk_fma_f32 v[116:117], v[76:77], v[34:35], v[116:117] op_sel:[1,0,0] op_sel_hi:[1,1,1]
	v_pk_fma_f32 v[122:123], v[78:79], v[34:35], v[122:123] op_sel:[0,0,0] op_sel_hi:[0,1,1]
	v_pk_fma_f32 v[124:125], v[78:79], v[34:35], v[124:125] op_sel:[1,0,0] op_sel_hi:[1,1,1]
	v_pk_fma_f32 v[126:127], v[80:81], v[34:35], v[126:127] op_sel:[0,0,0] op_sel_hi:[0,1,1]
	v_pk_fma_f32 v[128:129], v[80:81], v[34:35], v[128:129] op_sel:[1,0,0] op_sel_hi:[1,1,1]
	v_pk_fma_f32 v[130:131], v[82:83], v[34:35], v[130:131] op_sel:[0,0,0] op_sel_hi:[0,1,1]
	v_pk_fma_f32 v[132:133], v[82:83], v[34:35], v[132:133] op_sel:[1,0,0] op_sel_hi:[1,1,1]
	s_waitcnt lgkmcnt(6)
	v_pk_fma_f32 v[86:87], v[84:85], v[0:1], v[86:87] op_sel:[0,0,0] op_sel_hi:[1,0,1] neg_lo:[1,0,0] neg_hi:[1,0,0]
	v_pk_fma_f32 v[86:87], v[34:35], v[0:1], v[86:87] op_sel:[0,1,0] op_sel_hi:[1,1,1]
	s_mov_b64 exec, s[8:9]
	ds_write2_b32 v120, v86, v87 offset0:0 offset1:32
	s_mov_b64 exec, -1
	s_waitcnt lgkmcnt(5)
	v_pk_fma_f32 v[60:61], v[60:61], v[18:19], v[114:115] op_sel:[0,0,0] op_sel_hi:[1,0,1]
	v_pk_fma_f32 v[62:63], v[62:63], v[18:19], v[116:117] op_sel:[0,1,0] op_sel_hi:[1,1,1]
	v_pk_fma_f32 v[64:65], v[64:65], v[20:21], v[122:123] op_sel:[0,0,0] op_sel_hi:[1,0,1]
	v_pk_fma_f32 v[66:67], v[66:67], v[20:21], v[124:125] op_sel:[0,1,0] op_sel_hi:[1,1,1]
	v_pk_fma_f32 v[68:69], v[68:69], v[22:23], v[126:127] op_sel:[0,0,0] op_sel_hi:[1,0,1]
	v_pk_fma_f32 v[70:71], v[70:71], v[22:23], v[128:129] op_sel:[0,1,0] op_sel_hi:[1,1,1]
	v_pk_fma_f32 v[72:73], v[72:73], v[24:25], v[130:131] op_sel:[0,0,0] op_sel_hi:[1,0,1]
	v_pk_fma_f32 v[74:75], v[74:75], v[24:25], v[132:133] op_sel:[0,1,0] op_sel_hi:[1,1,1]
	ds_read_b128 v[26:29], v118 offset:41216
	ds_read_b128 v[30:33], v118 offset:41232
	ds_read_b128 v[76:79], v118 offset:16640
	ds_read_b128 v[80:83], v118 offset:16656
	ds_read2_b32 v[34:35], v119 offset0:64 offset1:96
	ds_read2_b32 v[0:1], v121 offset0:1 offset1:33
	ds_read_b128 v[18:21], v118 offset:8448
	ds_read_b128 v[22:25], v118 offset:8464
	s_waitcnt lgkmcnt(8)
	v_pk_mul_f32 v[84:85], v[60:61], v[2:3] op_sel:[0,0] op_sel_hi:[1,0]
	v_pk_mul_f32 v[86:87], v[60:61], v[10:11] op_sel:[0,0] op_sel_hi:[1,0]
	v_pk_fma_f32 v[84:85], v[62:63], v[2:3], v[84:85] op_sel:[0,1,0] op_sel_hi:[1,1,1]
	v_pk_fma_f32 v[86:87], v[62:63], v[10:11], v[86:87] op_sel:[0,1,0] op_sel_hi:[1,1,1]
	v_pk_fma_f32 v[84:85], v[64:65], v[4:5], v[84:85] op_sel:[0,0,0] op_sel_hi:[1,0,1]
	v_pk_fma_f32 v[86:87], v[64:65], v[12:13], v[86:87] op_sel:[0,0,0] op_sel_hi:[1,0,1]
	v_pk_fma_f32 v[84:85], v[66:67], v[4:5], v[84:85] op_sel:[0,1,0] op_sel_hi:[1,1,1]
	v_pk_fma_f32 v[86:87], v[66:67], v[12:13], v[86:87] op_sel:[0,1,0] op_sel_hi:[1,1,1]
	v_pk_fma_f32 v[84:85], v[68:69], v[6:7], v[84:85] op_sel:[0,0,0] op_sel_hi:[1,0,1]
	v_pk_fma_f32 v[86:87], v[68:69], v[14:15], v[86:87] op_sel:[0,0,0] op_sel_hi:[1,0,1]
	v_pk_fma_f32 v[84:85], v[70:71], v[6:7], v[84:85] op_sel:[0,1,0] op_sel_hi:[1,1,1]
	v_pk_fma_f32 v[86:87], v[70:71], v[14:15], v[86:87] op_sel:[0,1,0] op_sel_hi:[1,1,1]
	v_pk_fma_f32 v[84:85], v[72:73], v[8:9], v[84:85] op_sel:[0,0,0] op_sel_hi:[1,0,1]
	v_pk_fma_f32 v[86:87], v[72:73], v[16:17], v[86:87] op_sel:[0,0,0] op_sel_hi:[1,0,1]
	v_pk_fma_f32 v[84:85], v[74:75], v[8:9], v[84:85] op_sel:[0,1,0] op_sel_hi:[1,1,1]
	v_pk_fma_f32 v[86:87], v[74:75], v[16:17], v[86:87] op_sel:[0,1,0] op_sel_hi:[1,1,1]
	v_add_f32_dpp v84, v84, v84 quad_perm:[1,0,3,2] row_mask:0xf bank_mask:0xf bound_ctrl:1
	v_add_f32_dpp v85, v85, v85 quad_perm:[1,0,3,2] row_mask:0xf bank_mask:0xf bound_ctrl:1
	v_add_f32_dpp v86, v86, v86 quad_perm:[1,0,3,2] row_mask:0xf bank_mask:0xf bound_ctrl:1
	v_add_f32_dpp v87, v87, v87 quad_perm:[1,0,3,2] row_mask:0xf bank_mask:0xf bound_ctrl:1
	v_add_f32_dpp v84, v84, v84 quad_perm:[2,3,0,1] row_mask:0xf bank_mask:0xf bound_ctrl:1
	v_add_f32_dpp v85, v85, v85 quad_perm:[2,3,0,1] row_mask:0xf bank_mask:0xf bound_ctrl:1
	v_add_f32_dpp v86, v86, v86 quad_perm:[2,3,0,1] row_mask:0xf bank_mask:0xf bound_ctrl:1
	v_add_f32_dpp v87, v87, v87 quad_perm:[2,3,0,1] row_mask:0xf bank_mask:0xf bound_ctrl:1
	v_add_f32_dpp v84, v84, v84 row_half_mirror row_mask:0xf bank_mask:0xf bound_ctrl:1
	v_add_f32_dpp v85, v85, v85 row_half_mirror row_mask:0xf bank_mask:0xf bound_ctrl:1
	v_add_f32_dpp v86, v86, v86 row_half_mirror row_mask:0xf bank_mask:0xf bound_ctrl:1
	v_add_f32_dpp v87, v87, v87 row_half_mirror row_mask:0xf bank_mask:0xf bound_ctrl:1
	ds_read_b128 v[2:5], v118 offset:33280
	ds_read_b128 v[6:9], v118 offset:33296
	ds_read_b128 v[10:13], v118 offset:512
	ds_read_b128 v[14:17], v118 offset:528
	s_waitcnt lgkmcnt(10)
	v_pk_mul_f32 v[114:115], v[26:27], v[84:85] op_sel:[0,0] op_sel_hi:[0,1] neg_lo:[0,1] neg_hi:[0,1]
	v_pk_mul_f32 v[116:117], v[26:27], v[84:85] op_sel:[1,0] op_sel_hi:[1,1] neg_lo:[0,1] neg_hi:[0,1]
	v_pk_mul_f32 v[122:123], v[28:29], v[84:85] op_sel:[0,0] op_sel_hi:[0,1] neg_lo:[0,1] neg_hi:[0,1]
	v_pk_mul_f32 v[124:125], v[28:29], v[84:85] op_sel:[1,0] op_sel_hi:[1,1] neg_lo:[0,1] neg_hi:[0,1]
	v_pk_mul_f32 v[126:127], v[30:31], v[84:85] op_sel:[0,0] op_sel_hi:[0,1] neg_lo:[0,1] neg_hi:[0,1]
	v_pk_mul_f32 v[128:129], v[30:31], v[84:85] op_sel:[1,0] op_sel_hi:[1,1] neg_lo:[0,1] neg_hi:[0,1]
	v_pk_mul_f32 v[130:131], v[32:33], v[84:85] op_sel:[0,0] op_sel_hi:[0,1] neg_lo:[0,1] neg_hi:[0,1]
	v_pk_mul_f32 v[132:133], v[32:33], v[84:85] op_sel:[1,0] op_sel_hi:[1,1] neg_lo:[0,1] neg_hi:[0,1]
	s_waitcnt lgkmcnt(7)
	v_pk_fma_f32 v[114:115], v[76:77], v[34:35], v[114:115] op_sel:[0,0,0] op_sel_hi:[0,1,1]
	v_pk_fma_f32 v[116:117], v[76:77], v[34:35], v[116:117] op_sel:[1,0,0] op_sel_hi:[1,1,1]
	v_pk_fma_f32 v[122:123], v[78:79], v[34:35], v[122:123] op_sel:[0,0,0] op_sel_hi:[0,1,1]
	v_pk_fma_f32 v[124:125], v[78:79], v[34:35], v[124:125] op_sel:[1,0,0] op_sel_hi:[1,1,1]
	v_pk_fma_f32 v[126:127], v[80:81], v[34:35], v[126:127] op_sel:[0,0,0] op_sel_hi:[0,1,1]
	v_pk_fma_f32 v[128:129], v[80:81], v[34:35], v[128:129] op_sel:[1,0,0] op_sel_hi:[1,1,1]
	v_pk_fma_f32 v[130:131], v[82:83], v[34:35], v[130:131] op_sel:[0,0,0] op_sel_hi:[0,1,1]
	v_pk_fma_f32 v[132:133], v[82:83], v[34:35], v[132:133] op_sel:[1,0,0] op_sel_hi:[1,1,1]
	s_waitcnt lgkmcnt(6)
	v_pk_fma_f32 v[86:87], v[84:85], v[0:1], v[86:87] op_sel:[0,0,0] op_sel_hi:[1,0,1] neg_lo:[1,0,0] neg_hi:[1,0,0]
	v_pk_fma_f32 v[86:87], v[34:35], v[0:1], v[86:87] op_sel:[0,1,0] op_sel_hi:[1,1,1]
	s_mov_b64 exec, s[8:9]
	ds_write2_b32 v120, v86, v87 offset0:64 offset1:96
	s_mov_b64 exec, -1
	s_waitcnt lgkmcnt(5)
	v_pk_fma_f32 v[60:61], v[60:61], v[18:19], v[114:115] op_sel:[0,0,0] op_sel_hi:[1,0,1]
	v_pk_fma_f32 v[62:63], v[62:63], v[18:19], v[116:117] op_sel:[0,1,0] op_sel_hi:[1,1,1]
	v_pk_fma_f32 v[64:65], v[64:65], v[20:21], v[122:123] op_sel:[0,0,0] op_sel_hi:[1,0,1]
	v_pk_fma_f32 v[66:67], v[66:67], v[20:21], v[124:125] op_sel:[0,1,0] op_sel_hi:[1,1,1]
	v_pk_fma_f32 v[68:69], v[68:69], v[22:23], v[126:127] op_sel:[0,0,0] op_sel_hi:[1,0,1]
	v_pk_fma_f32 v[70:71], v[70:71], v[22:23], v[128:129] op_sel:[0,1,0] op_sel_hi:[1,1,1]
	v_pk_fma_f32 v[72:73], v[72:73], v[24:25], v[130:131] op_sel:[0,0,0] op_sel_hi:[1,0,1]
	v_pk_fma_f32 v[74:75], v[74:75], v[24:25], v[132:133] op_sel:[0,1,0] op_sel_hi:[1,1,1]
	ds_read_b128 v[26:29], v118 offset:41472
	ds_read_b128 v[30:33], v118 offset:41488
	ds_read_b128 v[76:79], v118 offset:16896
	ds_read_b128 v[80:83], v118 offset:16912
	ds_read2_b32 v[34:35], v119 offset0:128 offset1:160
	ds_read2_b32 v[0:1], v121 offset0:2 offset1:34
	ds_read_b128 v[18:21], v118 offset:8704
	ds_read_b128 v[22:25], v118 offset:8720
	s_waitcnt lgkmcnt(8)
	v_pk_mul_f32 v[84:85], v[60:61], v[2:3] op_sel:[0,0] op_sel_hi:[1,0]
	v_pk_mul_f32 v[86:87], v[60:61], v[10:11] op_sel:[0,0] op_sel_hi:[1,0]
	v_pk_fma_f32 v[84:85], v[62:63], v[2:3], v[84:85] op_sel:[0,1,0] op_sel_hi:[1,1,1]
	v_pk_fma_f32 v[86:87], v[62:63], v[10:11], v[86:87] op_sel:[0,1,0] op_sel_hi:[1,1,1]
	v_pk_fma_f32 v[84:85], v[64:65], v[4:5], v[84:85] op_sel:[0,0,0] op_sel_hi:[1,0,1]
	v_pk_fma_f32 v[86:87], v[64:65], v[12:13], v[86:87] op_sel:[0,0,0] op_sel_hi:[1,0,1]
	v_pk_fma_f32 v[84:85], v[66:67], v[4:5], v[84:85] op_sel:[0,1,0] op_sel_hi:[1,1,1]
	v_pk_fma_f32 v[86:87], v[66:67], v[12:13], v[86:87] op_sel:[0,1,0] op_sel_hi:[1,1,1]
	v_pk_fma_f32 v[84:85], v[68:69], v[6:7], v[84:85] op_sel:[0,0,0] op_sel_hi:[1,0,1]
	v_pk_fma_f32 v[86:87], v[68:69], v[14:15], v[86:87] op_sel:[0,0,0] op_sel_hi:[1,0,1]
	v_pk_fma_f32 v[84:85], v[70:71], v[6:7], v[84:85] op_sel:[0,1,0] op_sel_hi:[1,1,1]
	v_pk_fma_f32 v[86:87], v[70:71], v[14:15], v[86:87] op_sel:[0,1,0] op_sel_hi:[1,1,1]
	v_pk_fma_f32 v[84:85], v[72:73], v[8:9], v[84:85] op_sel:[0,0,0] op_sel_hi:[1,0,1]
	v_pk_fma_f32 v[86:87], v[72:73], v[16:17], v[86:87] op_sel:[0,0,0] op_sel_hi:[1,0,1]
	v_pk_fma_f32 v[84:85], v[74:75], v[8:9], v[84:85] op_sel:[0,1,0] op_sel_hi:[1,1,1]
	v_pk_fma_f32 v[86:87], v[74:75], v[16:17], v[86:87] op_sel:[0,1,0] op_sel_hi:[1,1,1]
	v_add_f32_dpp v84, v84, v84 quad_perm:[1,0,3,2] row_mask:0xf bank_mask:0xf bound_ctrl:1
	v_add_f32_dpp v85, v85, v85 quad_perm:[1,0,3,2] row_mask:0xf bank_mask:0xf bound_ctrl:1
	v_add_f32_dpp v86, v86, v86 quad_perm:[1,0,3,2] row_mask:0xf bank_mask:0xf bound_ctrl:1
	v_add_f32_dpp v87, v87, v87 quad_perm:[1,0,3,2] row_mask:0xf bank_mask:0xf bound_ctrl:1
	v_add_f32_dpp v84, v84, v84 quad_perm:[2,3,0,1] row_mask:0xf bank_mask:0xf bound_ctrl:1
	v_add_f32_dpp v85, v85, v85 quad_perm:[2,3,0,1] row_mask:0xf bank_mask:0xf bound_ctrl:1
	v_add_f32_dpp v86, v86, v86 quad_perm:[2,3,0,1] row_mask:0xf bank_mask:0xf bound_ctrl:1
	v_add_f32_dpp v87, v87, v87 quad_perm:[2,3,0,1] row_mask:0xf bank_mask:0xf bound_ctrl:1
	v_add_f32_dpp v84, v84, v84 row_half_mirror row_mask:0xf bank_mask:0xf bound_ctrl:1
	v_add_f32_dpp v85, v85, v85 row_half_mirror row_mask:0xf bank_mask:0xf bound_ctrl:1
	v_add_f32_dpp v86, v86, v86 row_half_mirror row_mask:0xf bank_mask:0xf bound_ctrl:1
	v_add_f32_dpp v87, v87, v87 row_half_mirror row_mask:0xf bank_mask:0xf bound_ctrl:1
	ds_read_b128 v[2:5], v118 offset:33536
	ds_read_b128 v[6:9], v118 offset:33552
	ds_read_b128 v[10:13], v118 offset:768
	ds_read_b128 v[14:17], v118 offset:784
	s_waitcnt lgkmcnt(10)
	v_pk_mul_f32 v[114:115], v[26:27], v[84:85] op_sel:[0,0] op_sel_hi:[0,1] neg_lo:[0,1] neg_hi:[0,1]
	v_pk_mul_f32 v[116:117], v[26:27], v[84:85] op_sel:[1,0] op_sel_hi:[1,1] neg_lo:[0,1] neg_hi:[0,1]
	v_pk_mul_f32 v[122:123], v[28:29], v[84:85] op_sel:[0,0] op_sel_hi:[0,1] neg_lo:[0,1] neg_hi:[0,1]
	v_pk_mul_f32 v[124:125], v[28:29], v[84:85] op_sel:[1,0] op_sel_hi:[1,1] neg_lo:[0,1] neg_hi:[0,1]
	v_pk_mul_f32 v[126:127], v[30:31], v[84:85] op_sel:[0,0] op_sel_hi:[0,1] neg_lo:[0,1] neg_hi:[0,1]
	v_pk_mul_f32 v[128:129], v[30:31], v[84:85] op_sel:[1,0] op_sel_hi:[1,1] neg_lo:[0,1] neg_hi:[0,1]
	v_pk_mul_f32 v[130:131], v[32:33], v[84:85] op_sel:[0,0] op_sel_hi:[0,1] neg_lo:[0,1] neg_hi:[0,1]
	v_pk_mul_f32 v[132:133], v[32:33], v[84:85] op_sel:[1,0] op_sel_hi:[1,1] neg_lo:[0,1] neg_hi:[0,1]
	s_waitcnt lgkmcnt(7)
	v_pk_fma_f32 v[114:115], v[76:77], v[34:35], v[114:115] op_sel:[0,0,0] op_sel_hi:[0,1,1]
	v_pk_fma_f32 v[116:117], v[76:77], v[34:35], v[116:117] op_sel:[1,0,0] op_sel_hi:[1,1,1]
	v_pk_fma_f32 v[122:123], v[78:79], v[34:35], v[122:123] op_sel:[0,0,0] op_sel_hi:[0,1,1]
	v_pk_fma_f32 v[124:125], v[78:79], v[34:35], v[124:125] op_sel:[1,0,0] op_sel_hi:[1,1,1]
	v_pk_fma_f32 v[126:127], v[80:81], v[34:35], v[126:127] op_sel:[0,0,0] op_sel_hi:[0,1,1]
	v_pk_fma_f32 v[128:129], v[80:81], v[34:35], v[128:129] op_sel:[1,0,0] op_sel_hi:[1,1,1]
	v_pk_fma_f32 v[130:131], v[82:83], v[34:35], v[130:131] op_sel:[0,0,0] op_sel_hi:[0,1,1]
	v_pk_fma_f32 v[132:133], v[82:83], v[34:35], v[132:133] op_sel:[1,0,0] op_sel_hi:[1,1,1]
	s_waitcnt lgkmcnt(6)
	v_pk_fma_f32 v[86:87], v[84:85], v[0:1], v[86:87] op_sel:[0,0,0] op_sel_hi:[1,0,1] neg_lo:[1,0,0] neg_hi:[1,0,0]
	v_pk_fma_f32 v[86:87], v[34:35], v[0:1], v[86:87] op_sel:[0,1,0] op_sel_hi:[1,1,1]
	s_mov_b64 exec, s[8:9]
	ds_write2_b32 v120, v86, v87 offset0:128 offset1:160
	s_mov_b64 exec, -1
	s_waitcnt lgkmcnt(5)
	v_pk_fma_f32 v[60:61], v[60:61], v[18:19], v[114:115] op_sel:[0,0,0] op_sel_hi:[1,0,1]
	v_pk_fma_f32 v[62:63], v[62:63], v[18:19], v[116:117] op_sel:[0,1,0] op_sel_hi:[1,1,1]
	v_pk_fma_f32 v[64:65], v[64:65], v[20:21], v[122:123] op_sel:[0,0,0] op_sel_hi:[1,0,1]
	v_pk_fma_f32 v[66:67], v[66:67], v[20:21], v[124:125] op_sel:[0,1,0] op_sel_hi:[1,1,1]
	v_pk_fma_f32 v[68:69], v[68:69], v[22:23], v[126:127] op_sel:[0,0,0] op_sel_hi:[1,0,1]
	v_pk_fma_f32 v[70:71], v[70:71], v[22:23], v[128:129] op_sel:[0,1,0] op_sel_hi:[1,1,1]
	v_pk_fma_f32 v[72:73], v[72:73], v[24:25], v[130:131] op_sel:[0,0,0] op_sel_hi:[1,0,1]
	v_pk_fma_f32 v[74:75], v[74:75], v[24:25], v[132:133] op_sel:[0,1,0] op_sel_hi:[1,1,1]
	ds_read_b128 v[26:29], v118 offset:41728
	ds_read_b128 v[30:33], v118 offset:41744
	ds_read_b128 v[76:79], v118 offset:17152
	ds_read_b128 v[80:83], v118 offset:17168
	ds_read2_b32 v[34:35], v119 offset0:192 offset1:224
	ds_read2_b32 v[0:1], v121 offset0:3 offset1:35
	ds_read_b128 v[18:21], v118 offset:8960
	ds_read_b128 v[22:25], v118 offset:8976
	s_waitcnt lgkmcnt(8)
; #define SCAN_LDK(X, X0, X1, s_) do { const LAS float* p_ = ib + (s_) * 64 + kp; \
;                     X[0] = *(const LAS f32x4*)(p_ + 4 * CH * 64); X[1] = *(const LAS f32x4*)(p_ + 4 * CH * 64 + 4); \
;                     X0 = ib[3 * CH * 64 + (s_) * 64 + v0]; X1 = ib[3 * CH * 64 + (s_) * 64 + v1]; } while (0)
; DEVINL void rwkv_scan(LAS unsigned char* lds, const bf16_t* Prwkv, const bf16_t* Aa, const bf16_t* Gg, const bf16_t* Uu, const float* w0v, const float* a0v, const float* mu, ...
;     ...
;                 __builtin_amdgcn_s_setprio(2);
;                 SCAN_LDK(Ka, Av0, Av1, 0);
; #pragma unroll 1
;                 for (int s = 0; s < CH; s += 2) {
;                     SCAN_STEP(Ka, Av0, Av1, s, SCAN_LDK(Kb, Bv0, Bv1, s + 1));
;                     const int sn = (s + 2 < CH) ? s + 2 : CH - 1;
;                     SCAN_STEP(Kb, Bv0, Bv1, s + 1, SCAN_LDK(Ka, Av0, Av1, sn));
;                 }
;                 __builtin_amdgcn_s_setprio(0);
;     ...
;             }
;             __syncthreads();
	v_pk_mul_f32 v[84:85], v[60:61], v[2:3] op_sel:[0,0] op_sel_hi:[1,0]
	v_pk_mul_f32 v[86:87], v[60:61], v[10:11] op_sel:[0,0] op_sel_hi:[1,0]
	v_pk_fma_f32 v[84:85], v[62:63], v[2:3], v[84:85] op_sel:[0,1,0] op_sel_hi:[1,1,1]
	v_pk_fma_f32 v[86:87], v[62:63], v[10:11], v[86:87] op_sel:[0,1,0] op_sel_hi:[1,1,1]
	v_pk_fma_f32 v[84:85], v[64:65], v[4:5], v[84:85] op_sel:[0,0,0] op_sel_hi:[1,0,1]
	v_pk_fma_f32 v[86:87], v[64:65], v[12:13], v[86:87] op_sel:[0,0,0] op_sel_hi:[1,0,1]
	v_pk_fma_f32 v[84:85], v[66:67], v[4:5], v[84:85] op_sel:[0,1,0] op_sel_hi:[1,1,1]
	v_pk_fma_f32 v[86:87], v[66:67], v[12:13], v[86:87] op_sel:[0,1,0] op_sel_hi:[1,1,1]
	v_pk_fma_f32 v[84:85], v[68:69], v[6:7], v[84:85] op_sel:[0,0,0] op_sel_hi:[1,0,1]
	v_pk_fma_f32 v[86:87], v[68:69], v[14:15], v[86:87] op_sel:[0,0,0] op_sel_hi:[1,0,1]
	v_pk_fma_f32 v[84:85], v[70:71], v[6:7], v[84:85] op_sel:[0,1,0] op_sel_hi:[1,1,1]
	v_pk_fma_f32 v[86:87], v[70:71], v[14:15], v[86:87] op_sel:[0,1,0] op_sel_hi:[1,1,1]
	v_pk_fma_f32 v[84:85], v[72:73], v[8:9], v[84:85] op_sel:[0,0,0] op_sel_hi:[1,0,1]
	v_pk_fma_f32 v[86:87], v[72:73], v[16:17], v[86:87] op_sel:[0,0,0] op_sel_hi:[1,0,1]
	v_pk_fma_f32 v[84:85], v[74:75], v[8:9], v[84:85] op_sel:[0,1,0] op_sel_hi:[1,1,1]
	v_pk_fma_f32 v[86:87], v[74:75], v[16:17], v[86:87] op_sel:[0,1,0] op_sel_hi:[1,1,1]
	v_add_f32_dpp v84, v84, v84 quad_perm:[1,0,3,2] row_mask:0xf bank_mask:0xf bound_ctrl:1
	v_add_f32_dpp v85, v85, v85 quad_perm:[1,0,3,2] row_mask:0xf bank_mask:0xf bound_ctrl:1
	v_add_f32_dpp v86, v86, v86 quad_perm:[1,0,3,2] row_mask:0xf bank_mask:0xf bound_ctrl:1
	v_add_f32_dpp v87, v87, v87 quad_perm:[1,0,3,2] row_mask:0xf bank_mask:0xf bound_ctrl:1
	v_add_f32_dpp v84, v84, v84 quad_perm:[2,3,0,1] row_mask:0xf bank_mask:0xf bound_ctrl:1
	v_add_f32_dpp v85, v85, v85 quad_perm:[2,3,0,1] row_mask:0xf bank_mask:0xf bound_ctrl:1
	v_add_f32_dpp v86, v86, v86 quad_perm:[2,3,0,1] row_mask:0xf bank_mask:0xf bound_ctrl:1
	v_add_f32_dpp v87, v87, v87 quad_perm:[2,3,0,1] row_mask:0xf bank_mask:0xf bound_ctrl:1
	v_add_f32_dpp v84, v84, v84 row_half_mirror row_mask:0xf bank_mask:0xf bound_ctrl:1
	v_add_f32_dpp v85, v85, v85 row_half_mirror row_mask:0xf bank_mask:0xf bound_ctrl:1
	v_add_f32_dpp v86, v86, v86 row_half_mirror row_mask:0xf bank_mask:0xf bound_ctrl:1
	v_add_f32_dpp v87, v87, v87 row_half_mirror row_mask:0xf bank_mask:0xf bound_ctrl:1
	ds_read_b128 v[2:5], v118 offset:33792
	ds_read_b128 v[6:9], v118 offset:33808
	ds_read_b128 v[10:13], v118 offset:1024
	ds_read_b128 v[14:17], v118 offset:1040
	s_waitcnt lgkmcnt(10)
	v_pk_mul_f32 v[114:115], v[26:27], v[84:85] op_sel:[0,0] op_sel_hi:[0,1] neg_lo:[0,1] neg_hi:[0,1]
	v_pk_mul_f32 v[116:117], v[26:27], v[84:85] op_sel:[1,0] op_sel_hi:[1,1] neg_lo:[0,1] neg_hi:[0,1]
	v_pk_mul_f32 v[122:123], v[28:29], v[84:85] op_sel:[0,0] op_sel_hi:[0,1] neg_lo:[0,1] neg_hi:[0,1]
	v_pk_mul_f32 v[124:125], v[28:29], v[84:85] op_sel:[1,0] op_sel_hi:[1,1] neg_lo:[0,1] neg_hi:[0,1]
	v_pk_mul_f32 v[126:127], v[30:31], v[84:85] op_sel:[0,0] op_sel_hi:[0,1] neg_lo:[0,1] neg_hi:[0,1]
	v_pk_mul_f32 v[128:129], v[30:31], v[84:85] op_sel:[1,0] op_sel_hi:[1,1] neg_lo:[0,1] neg_hi:[0,1]
	v_pk_mul_f32 v[130:131], v[32:33], v[84:85] op_sel:[0,0] op_sel_hi:[0,1] neg_lo:[0,1] neg_hi:[0,1]
	v_pk_mul_f32 v[132:133], v[32:33], v[84:85] op_sel:[1,0] op_sel_hi:[1,1] neg_lo:[0,1] neg_hi:[0,1]
	s_waitcnt lgkmcnt(7)
	v_pk_fma_f32 v[114:115], v[76:77], v[34:35], v[114:115] op_sel:[0,0,0] op_sel_hi:[0,1,1]
	v_pk_fma_f32 v[116:117], v[76:77], v[34:35], v[116:117] op_sel:[1,0,0] op_sel_hi:[1,1,1]
	v_pk_fma_f32 v[122:123], v[78:79], v[34:35], v[122:123] op_sel:[0,0,0] op_sel_hi:[0,1,1]
	v_pk_fma_f32 v[124:125], v[78:79], v[34:35], v[124:125] op_sel:[1,0,0] op_sel_hi:[1,1,1]
	v_pk_fma_f32 v[126:127], v[80:81], v[34:35], v[126:127] op_sel:[0,0,0] op_sel_hi:[0,1,1]
	v_pk_fma_f32 v[128:129], v[80:81], v[34:35], v[128:129] op_sel:[1,0,0] op_sel_hi:[1,1,1]
	v_pk_fma_f32 v[130:131], v[82:83], v[34:35], v[130:131] op_sel:[0,0,0] op_sel_hi:[0,1,1]
	v_pk_fma_f32 v[132:133], v[82:83], v[34:35], v[132:133] op_sel:[1,0,0] op_sel_hi:[1,1,1]
	s_waitcnt lgkmcnt(6)
	v_pk_fma_f32 v[86:87], v[84:85], v[0:1], v[86:87] op_sel:[0,0,0] op_sel_hi:[1,0,1] neg_lo:[1,0,0] neg_hi:[1,0,0]
	v_pk_fma_f32 v[86:87], v[34:35], v[0:1], v[86:87] op_sel:[0,1,0] op_sel_hi:[1,1,1]
	s_mov_b64 exec, s[8:9]
	ds_write2_b32 v120, v86, v87 offset0:192 offset1:224
	s_mov_b64 exec, -1
	s_waitcnt lgkmcnt(5)
	v_pk_fma_f32 v[60:61], v[60:61], v[18:19], v[114:115] op_sel:[0,0,0] op_sel_hi:[1,0,1]
	v_pk_fma_f32 v[62:63], v[62:63], v[18:19], v[116:117] op_sel:[0,1,0] op_sel_hi:[1,1,1]
	v_pk_fma_f32 v[64:65], v[64:65], v[20:21], v[122:123] op_sel:[0,0,0] op_sel_hi:[1,0,1]
	v_pk_fma_f32 v[66:67], v[66:67], v[20:21], v[124:125] op_sel:[0,1,0] op_sel_hi:[1,1,1]
	v_pk_fma_f32 v[68:69], v[68:69], v[22:23], v[126:127] op_sel:[0,0,0] op_sel_hi:[1,0,1]
	v_pk_fma_f32 v[70:71], v[70:71], v[22:23], v[128:129] op_sel:[0,1,0] op_sel_hi:[1,1,1]
	v_pk_fma_f32 v[72:73], v[72:73], v[24:25], v[130:131] op_sel:[0,0,0] op_sel_hi:[1,0,1]
	v_pk_fma_f32 v[74:75], v[74:75], v[24:25], v[132:133] op_sel:[0,1,0] op_sel_hi:[1,1,1]
	v_add_u32_e32 v118, 0x400, v118
	v_add_u32_e32 v119, 0x400, v119
	v_add_u32_e32 v120, 0x400, v120
	v_add_u32_e32 v121, 16, v121
	s_add_i32 s44, s44, 1
	s_cmp_lt_u32 s44, 8
	s_cbranch_scc1 .Lscan_iter
	s_setprio 0
	s_add_i32 s30, s30, 1
	s_cmp_eq_u32 s30, 64
	s_waitcnt lgkmcnt(0)
	s_barrier
	s_cbranch_scc0 .Lscan_chunk
	s_branch .LBB0_1087
